# prompt attention: next-tile K/V global loads issued one at a time between the QK/PV MFMAs (running pointers) instead of a 10-load burst after the barrier
# speedup vs baseline: 1.0074x; 1.0074x over previous
; template <int DK, int DV, int KT, bool SAMPLE>
; DI void attn_item(CP c, int l, int qb, int h, unsigned char* sm) {
;     ...
;     u32x4 kreg[6], vreg[4];
;     const int lkey = gt >> 2, ls0 = gt & 3, ldv = gt >> 1, lv0 = gt & 1;
;     const bf16_t* kn_base = KNg + (size_t)lkey * 512 + h * 128 + ls0 * 8; const bf16_t* kp_base = KPEg + (size_t)lkey * 64 + ls0 * 8;
;     const bf16_t* vt_base = VTg + (size_t)(h * 128 + ldv) * MP + lv0 * 8;
;     ...
;     if (!SAMPLE) ATT_ISSUE(g);
.LBB0_645:
	s_or_b64 exec, exec, s[12:13]
	v_bfe_u32 v8, v167, 2, 6
	v_lshlrev_b32_e32 v0, 10, v8
	v_ashrrev_i32_e32 v154, 8, v167
	v_lshl_add_u64 v[2:3], s[54:55], 0, v[0:1]
	v_lshlrev_b32_e32 v152, 7, v5
	v_lshlrev_b32_e32 v0, 8, v5
	v_lshlrev_b32_e32 v5, 4, v167
	v_lshl_add_u64 v[2:3], v[2:3], 0, v[0:1]
	v_and_b32_e32 v0, 48, v5
	v_ashrrev_i32_e32 v155, 31, v154
	v_lshl_add_u64 v[156:157], v[2:3], 0, v[0:1]
	v_lshlrev_b32_e32 v2, 7, v8
	v_mov_b32_e32 v3, v1
	v_lshlrev_b64 v[6:7], 16, v[154:155]
	v_bfe_u32 v9, v167, 1, 7
	v_lshl_add_u64 v[2:3], s[56:57], 0, v[2:3]
	v_lshl_add_u64 v[6:7], v[156:157], 0, v[6:7]
	v_or_b32_e32 v10, v9, v152
	global_load_dwordx4 v[112:115], v[6:7], off
	global_load_dwordx4 v[116:119], v[6:7], off offset:64
	global_load_dwordx4 v[120:123], v[6:7], off offset:128
	global_load_dwordx4 v[124:127], v[6:7], off offset:192
	v_lshl_add_u64 v[158:159], v[2:3], 0, v[0:1]
	v_lshlrev_b64 v[6:7], 13, v[154:155]
	v_lshlrev_b32_e32 v2, 15, v10
	v_mov_b32_e32 v3, v1
	v_lshl_add_u64 v[6:7], v[158:159], 0, v[6:7]
	v_lshl_add_u64 v[2:3], s[58:59], 0, v[2:3]
	global_load_dwordx4 v[128:131], v[6:7], off
	global_load_dwordx4 v[132:135], v[6:7], off offset:64
	v_and_b32_e32 v6, 16, v5
	v_mov_b32_e32 v7, v1
	v_lshl_add_u64 v[164:165], v[2:3], 0, v[6:7]
	v_lshlrev_b64 v[2:3], 7, v[154:155]
	v_lshl_add_u64 v[2:3], v[164:165], 0, v[2:3]
	global_load_dwordx4 v[136:139], v[2:3], off
	global_load_dwordx4 v[140:143], v[2:3], off offset:32
	global_load_dwordx4 v[144:147], v[2:3], off offset:64
	global_load_dwordx4 v[148:151], v[2:3], off offset:96
	s_mov_b32 s12, 0xac00
	v_bfe_u32 v173, v167, 6, 2
	v_bfe_u32 v155, v167, 5, 1
	v_mad_i32_i24 v2, v154, s12, 0
	v_lshrrev_b32_e32 v172, 6, v167
	v_add_u32_e32 v3, 0xc800, v2
	v_add_u32_e32 v16, v2, v0
	v_lshlrev_b32_e32 v20, 4, v155
	v_lshl_or_b32 v0, v173, 5, v166
	v_bfe_u32 v5, v172, 1, 1
	v_add_u32_e32 v17, v3, v6
	v_mul_u32_u24_e32 v18, 0x190, v8
	v_mul_u32_u24_e32 v19, 0x90, v9
	v_add_u32_e32 v21, v2, v20
	v_mad_u32_u24 v22, v0, s14, 0
	v_lshl_add_u32 v23, v155, 3, v3
	v_mul_u32_u24_e32 v24, 0x190, v166
	v_mul_u32_u24_e32 v25, 0x90, v166
	v_mov_b32_e32 v14, v1
	v_mov_b32_e32 v15, v1
	v_lshl_or_b32 v175, v171, 1, v5
	v_sub_u32_e32 v176, 0x80, v4
	v_mov_b32_e32 v0, v1
	v_mov_b32_e32 v2, v1
	v_mov_b32_e32 v3, v1
	v_mov_b32_e32 v4, v1
	v_mov_b32_e32 v5, v1
	v_mov_b32_e32 v6, v1
	v_mov_b32_e32 v8, v1
	v_mov_b32_e32 v9, v1
	v_mov_b32_e32 v10, v1
	v_mov_b32_e32 v11, v1
	v_mov_b32_e32 v12, v1
	v_mov_b32_e32 v13, v1
	v_add_u32_e32 v178, v16, v18
	v_add_u32_e32 v179, v17, v19
	v_add_u32_e32 v180, v21, v24
	v_add_u32_e32 v181, v22, v20
	v_add_u32_e32 v182, v23, v25
	v_mov_b64_e32 v[30:31], v[14:15]
	v_mov_b64_e32 v[46:47], v[14:15]
	v_mov_b64_e32 v[62:63], v[14:15]
	v_mov_b64_e32 v[78:79], v[14:15]
	v_and_b32_e32 v174, 63, v167
	s_mov_b32 s14, 0
	v_mov_b32_e32 v183, 0xff800000
	v_mov_b32_e32 v177, 0
	s_mov_b64 s[12:13], 0
	v_mov_b32_e32 v80, v154
	v_mov_b64_e32 v[28:29], v[12:13]
	v_mov_b64_e32 v[26:27], v[10:11]
	v_mov_b64_e32 v[24:25], v[8:9]
	v_mov_b64_e32 v[22:23], v[6:7]
	v_mov_b64_e32 v[20:21], v[4:5]
	v_mov_b64_e32 v[18:19], v[2:3]
	v_mov_b64_e32 v[16:17], v[0:1]
	v_mov_b64_e32 v[44:45], v[12:13]
	v_mov_b64_e32 v[42:43], v[10:11]
	v_mov_b64_e32 v[40:41], v[8:9]
	v_mov_b64_e32 v[38:39], v[6:7]
	v_mov_b64_e32 v[36:37], v[4:5]
	v_mov_b64_e32 v[34:35], v[2:3]
	v_mov_b64_e32 v[32:33], v[0:1]
	v_mov_b64_e32 v[60:61], v[12:13]
	v_mov_b64_e32 v[58:59], v[10:11]
	v_mov_b64_e32 v[56:57], v[8:9]
	v_mov_b64_e32 v[54:55], v[6:7]
	v_mov_b64_e32 v[52:53], v[4:5]
	v_mov_b64_e32 v[50:51], v[2:3]
	v_mov_b64_e32 v[48:49], v[0:1]
	v_mov_b64_e32 v[76:77], v[12:13]
	v_mov_b64_e32 v[74:75], v[10:11]
	v_mov_b64_e32 v[72:73], v[8:9]
	v_mov_b64_e32 v[70:71], v[6:7]
	v_mov_b64_e32 v[68:69], v[4:5]
	v_mov_b64_e32 v[66:67], v[2:3]
	v_mov_b64_e32 v[64:65], v[0:1]
	v_readfirstlane_b32 s32, v154
	s_mov_b32 s41, 0
	s_lshl_b32 s40, s32, 16
	v_lshl_add_u64 v[156:157], v[156:157], 0, s[40:41]
	s_lshl_b32 s40, s32, 13
	v_lshl_add_u64 v[158:159], v[158:159], 0, s[40:41]
	s_lshl_b32 s40, s32, 7
	v_lshl_add_u64 v[164:165], v[164:165], 0, s[40:41]
	s_mov_b32 s40, 0x20000
	s_mov_b32 s42, 0x4000
	s_mov_b32 s43, 0
	s_movk_i32 s88, 0x100
	s_mov_b32 s89, 0
	s_branch .LBB0_647

; template <int DK, int DV, int KT, bool SAMPLE>
; DI void attn_item(CP c, int l, int qb, int h, unsigned char* sm) {
;     ...
;         lds_barrier();
;         if (!SAMPLE) {
; #pragma unroll
;             for (int i = 0; i < 6; ++i) *(u32x4*)(Ks + lkey * QS + ls0 * 8 + i * 32) = kreg[i];
; #pragma unroll
;             for (int i = 0; i < 4; ++i) *(u32x4*)(Vs + ldv * VS + lv0 * 8 + i * 16) = vreg[i];
;         } else {
;             const int k0 = kt * 32;
;             for (int v = gt; v < 32 * 40; v += 256) { const int key = v / 40, s = v % 40, kk = k0 + key; u32x4 o = (u32x4){0u, 0u, 0u, 0u};
;                 if (kk < 2048) { const float* src = s < 32 ? c->in[I_CLAT] + ((size_t)(l * 32 + b) * 2048 + kk) * 256 + s * 8 : c->in[I_CKPE] + ((size_t)(l * 32 + b) * 2048 + kk) * 64 + (s - 32) * 8;
;                     const f32x4 a = *(const f32x4*)src, bq = *(const f32x4*)(src + 4); o.x = pk2(a[0], a[1]); o.y = pk2(a[2], a[3]); o.z = pk2(bq[0], bq[1]); o.w = pk2(bq[2], bq[3]); }
;                 else if (kk < 2064) { const int rr = MP + b * 16 + (kk - 2048); o = *(const u32x4*)(s < 32 ? LATg + (size_t)rr * 256 + s * 8 : KPEg + (size_t)rr * 64 + (s - 32) * 8); }
;                 *(u32x4*)(Ks + key * QS + s * 8) = o; }
;             for (int v = gt; v < 256 * 4; v += 256) { const int dv = v >> 2, s = v & 3; u32x4 o = (u32x4){0u, 0u, 0u, 0u};
;                 if (k0 < LTS) o = *(const u32x4*)(LTg + ((size_t)b * 256 + dv) * LTS + k0 + s * 8);
;                 *(u32x4*)(Vs + dv * VS + s * 8) = o; }
;         }
;         lds_barrier();
;         if (!SAMPLE) { if (j + 1 < nj) ATT_ISSUE(kt + 2); }
;         const bool active = SAMPLE ? (wave_on && kt * 32 < 2064) : (kt <= qc);
;         if (active) {
;             f32x16 S[NMT];
; #pragma unroll
;             for (int mt = 0; mt < NMT; ++mt)
; #pragma unroll
;                 for (int i = 0; i < 16; ++i) S[mt][i] = 0.f;
;             {
;                 constexpr int NKP = DK / 32;
;                 bf16x8 Kf[2][2 * NMT]; bf16x8 Ql[2][2];
; #pragma unroll
;                 for (int e = 0; e < 2; ++e) {
; #pragma unroll
;                     for (int mt = 0; mt < NMT; ++mt) Kf[0][e * NMT + mt] = *(const bf16x8*)(Ks + (32 * mt + l31) * QS + 16 * e + 8 * hh);
;                     if (!QREG) Ql[0][e] = *(const bf16x8*)(Qs + (32 * wq + l31) * QS + 16 * e + 8 * hh); }
; #pragma unroll
.LBB0_647:
	s_waitcnt lgkmcnt(0)
	s_barrier
	s_waitcnt vmcnt(9)
	ds_write_b128 v178, v[112:115] offset:51200
	s_waitcnt vmcnt(8)
	ds_write_b128 v178, v[116:119] offset:51264
	s_waitcnt vmcnt(7)
	ds_write_b128 v178, v[120:123] offset:51328
	s_waitcnt vmcnt(6)
	ds_write_b128 v178, v[124:127] offset:51392
	s_waitcnt vmcnt(5)
	ds_write_b128 v178, v[128:131] offset:51456
	s_waitcnt vmcnt(4)
	ds_write_b128 v178, v[132:135] offset:51520
	s_waitcnt vmcnt(3)
	ds_write_b128 v179, v[136:139] offset:25600
	s_waitcnt vmcnt(2)
	ds_write_b128 v179, v[140:143] offset:25632
	s_waitcnt vmcnt(1)
	ds_write_b128 v179, v[144:147] offset:25664
	s_waitcnt vmcnt(0)
	ds_write_b128 v179, v[148:151] offset:25696
	s_waitcnt lgkmcnt(0)
	s_barrier
	v_cmp_lt_u32_e32 vcc, s14, v171
	v_add_u32_e32 v2, 2, v80
	s_and_saveexec_b64 s[16:17], vcc
	s_cbranch_execz .LBB0_649
	v_lshl_add_u64 v[156:157], v[156:157], 0, s[40:41]
	v_lshl_add_u64 v[158:159], v[158:159], 0, s[42:43]
	v_lshl_add_u64 v[164:165], v[164:165], 0, s[88:89]
	ds_read_b128 v[4:7], v180 offset:51200
	ds_read_b128 v[8:11], v180 offset:51232
	ds_read_b128 v[12:15], v180 offset:64000
	ds_read_b128 v[184:187], v180 offset:64032
	ds_read_b128 v[80:83], v181
	ds_read_b128 v[214:217], v181 offset:32
	ds_read_b128 v[218:221], v180 offset:51264
	ds_read_b128 v[222:225], v180 offset:51296
	ds_read_b128 v[226:229], v180 offset:64064
	ds_read_b128 v[230:233], v180 offset:64096
	ds_read_b128 v[234:237], v181 offset:64
	ds_read_b128 v[238:241], v181 offset:96
	s_waitcnt lgkmcnt(7)
	v_mfma_f32_32x32x16_bf16 v[96:111], v[4:7], v[80:83], 0
	v_mfma_f32_32x32x16_bf16 v[80:95], v[12:15], v[80:83], 0
	global_load_dwordx4 v[112:115], v[156:157], off
	s_waitcnt lgkmcnt(6)
	v_mfma_f32_32x32x16_bf16 v[96:111], v[8:11], v[214:217], v[96:111]
	v_mfma_f32_32x32x16_bf16 v[80:95], v[184:187], v[214:217], v[80:95]
	ds_read_b128 v[4:7], v180 offset:51328
	ds_read_b128 v[8:11], v180 offset:51360
	ds_read_b128 v[12:15], v180 offset:64128
	ds_read_b128 v[184:187], v180 offset:64160
	ds_read_b128 v[214:217], v181 offset:128
	ds_read_b128 v[242:245], v181 offset:160
	s_waitcnt lgkmcnt(7)
	v_mfma_f32_32x32x16_bf16 v[96:111], v[218:221], v[234:237], v[96:111]
	v_mfma_f32_32x32x16_bf16 v[80:95], v[226:229], v[234:237], v[80:95]
	global_load_dwordx4 v[116:119], v[156:157], off offset:64
	s_waitcnt lgkmcnt(6)
	v_mfma_f32_32x32x16_bf16 v[96:111], v[222:225], v[238:241], v[96:111]
	v_mfma_f32_32x32x16_bf16 v[80:95], v[230:233], v[238:241], v[80:95]
	ds_read_b128 v[218:221], v180 offset:51392
	ds_read_b128 v[222:225], v180 offset:51424
	ds_read_b128 v[226:229], v180 offset:64192
	ds_read_b128 v[230:233], v180 offset:64224
	ds_read_b128 v[234:237], v181 offset:192
	ds_read_b128 v[238:241], v181 offset:224
	s_waitcnt lgkmcnt(7)
	v_mfma_f32_32x32x16_bf16 v[96:111], v[4:7], v[214:217], v[96:111]
	v_mfma_f32_32x32x16_bf16 v[80:95], v[12:15], v[214:217], v[80:95]
	global_load_dwordx4 v[120:123], v[156:157], off offset:128
	s_waitcnt lgkmcnt(6)
	v_mfma_f32_32x32x16_bf16 v[96:111], v[8:11], v[242:245], v[96:111]
	v_mfma_f32_32x32x16_bf16 v[80:95], v[184:187], v[242:245], v[80:95]
	ds_read_b128 v[4:7], v180 offset:51456
	ds_read_b128 v[8:11], v180 offset:51488
	ds_read_b128 v[12:15], v180 offset:64256
	ds_read_b128 v[184:187], v180 offset:64288
	ds_read_b128 v[214:217], v181 offset:256
	ds_read_b128 v[242:245], v181 offset:288
	s_waitcnt lgkmcnt(7)
	v_mfma_f32_32x32x16_bf16 v[96:111], v[218:221], v[234:237], v[96:111]
	v_mfma_f32_32x32x16_bf16 v[80:95], v[226:229], v[234:237], v[80:95]
	global_load_dwordx4 v[124:127], v[156:157], off offset:192
	s_waitcnt lgkmcnt(6)
	v_mfma_f32_32x32x16_bf16 v[96:111], v[222:225], v[238:241], v[96:111]
	v_mfma_f32_32x32x16_bf16 v[80:95], v[230:233], v[238:241], v[80:95]
	ds_read_b128 v[218:221], v180 offset:51520
	ds_read_b128 v[222:225], v180 offset:51552
	ds_read_b128 v[226:229], v180 offset:64320
	ds_read_b128 v[230:233], v180 offset:64352
	ds_read_b128 v[234:237], v181 offset:320
	ds_read_b128 v[238:241], v181 offset:352
	s_waitcnt lgkmcnt(7)
	v_mfma_f32_32x32x16_bf16 v[96:111], v[4:7], v[214:217], v[96:111]
	v_mfma_f32_32x32x16_bf16 v[80:95], v[12:15], v[214:217], v[80:95]
	global_load_dwordx4 v[128:131], v[158:159], off
	s_waitcnt lgkmcnt(6)
	v_mfma_f32_32x32x16_bf16 v[96:111], v[8:11], v[242:245], v[96:111]
	v_mfma_f32_32x32x16_bf16 v[80:95], v[184:187], v[242:245], v[80:95]
	s_waitcnt lgkmcnt(1)
	v_mfma_f32_32x32x16_bf16 v[96:111], v[218:221], v[234:237], v[96:111]
	v_mfma_f32_32x32x16_bf16 v[80:95], v[226:229], v[234:237], v[80:95]
	global_load_dwordx4 v[132:135], v[158:159], off offset:64
	s_waitcnt lgkmcnt(0)
; DI unsigned pk2(float lo, float hi) { const hwf2_t v = {lo, hi}; const hwbf2_t b = __builtin_convertvector(v, hwbf2_t); return __builtin_bit_cast(unsigned, b); }
; #define ATT_LDV(buf, gi) do { const int _kg = (gi) / NDB, _db = (gi) % NDB; _Pragma("unroll") for (int d = 0; d < 4; ++d) { const bf16_t* vp = Vs + (32 * (4 * _db + d) + l31) * VS + 16 * _kg + 4 * hh; \
;                         const u32x2 lo = *(const u32x2*)vp, hi = *(const u32x2*)(vp + 8); Vf[buf][d].x = lo.x; Vf[buf][d].y = lo.y; Vf[buf][d].z = hi.x; Vf[buf][d].w = hi.y; } } while (0)
; template <int DK, int DV, int KT, bool SAMPLE>
; DI void attn_item(CP c, int l, int qb, int h, unsigned char* sm) {
;     ...
;             float mloc = -INFINITY;
; #pragma unroll
;             for (int mt = 0; mt < NMT; ++mt)
; #pragma unroll
;                 for (int i = 0; i < 16; ++i) { float s = S[mt][i] * scale;
;                     if (SAMPLE) { const int key = kt * KT + 32 * mt + (i & 3) + 8 * (i >> 2) + 4 * hh; if (key >= 2064) s = -INFINITY; }
;                     S[mt][i] = s; mloc = fmaxf(mloc, s); }
;             mloc = fmaxf(mloc, __shfl_xor(mloc, 32));
;             const float mnew = fmaxf(m_run, mloc); const float alpha = __builtin_amdgcn_exp2f(m_run - mnew); float psum = 0.f;
; #pragma unroll
;             for (int mt = 0; mt < NMT; ++mt)
; #pragma unroll
;                 for (int i = 0; i < 16; ++i) { const float p = __builtin_amdgcn_exp2f(S[mt][i] - mnew); S[mt][i] = p; psum += p; }
;             l_run = l_run * alpha + psum; m_run = mnew;
; #pragma unroll
;             for (int d = 0; d < NDT; ++d) Oacc[d] = Oacc[d] * alpha;
;             {
;                 constexpr int NDB = NDT / 4;
;                 constexpr int NG = 2 * NMT * NDB;
;                 u32x4 Vf[2][4];
;     ...
;                 ATT_LDV(0, 0);
; #pragma unroll
;                 for (int gi = 0; gi < NG; ++gi) { const int kg = gi / NDB, db = gi % NDB, mt = kg >> 1, s2 = kg & 1;
;                     if (gi + 1 < NG) ATT_LDV((gi + 1) & 1, gi + 1);
;                     u32x4 pw; pw.x = pk2(S[mt][8 * s2 + 0], S[mt][8 * s2 + 1]); pw.y = pk2(S[mt][8 * s2 + 2], S[mt][8 * s2 + 3]);
;                     pw.z = pk2(S[mt][8 * s2 + 4], S[mt][8 * s2 + 5]); pw.w = pk2(S[mt][8 * s2 + 6], S[mt][8 * s2 + 7]);
	v_mfma_f32_32x32x16_bf16 v[96:111], v[222:225], v[238:241], v[96:111]
	v_mfma_f32_32x32x16_bf16 v[80:95], v[230:233], v[238:241], v[80:95]
	s_nop 10
	s_mov_b32 s18, 0xff800000
	v_max3_f32 v0, v96, s18, v97
	v_max3_f32 v0, v0, v98, v99
	v_max3_f32 v0, v0, v100, v101
	v_max3_f32 v0, v0, v102, v103
	v_max3_f32 v0, v0, v104, v105
	v_max3_f32 v0, v0, v106, v107
	v_max3_f32 v0, v0, v108, v109
	v_max3_f32 v0, v0, v110, v111
	v_max3_f32 v0, v0, v80, v81
	v_max3_f32 v0, v0, v82, v83
	v_max3_f32 v0, v0, v84, v85
	v_max3_f32 v0, v0, v86, v87
	v_max3_f32 v0, v0, v88, v89
	v_max3_f32 v0, v0, v90, v91
	v_max3_f32 v0, v0, v92, v93
	v_max3_f32 v0, v0, v94, v95
	s_mov_b32 s18, 0x3dd53b94
	v_mul_f32_e32 v0, 0x3dd53b94, v0
	v_add_u32_e32 v226, 0x6000, v182
	v_mov_b32_e32 v3, v0
	v_mov_b32_e32 v4, v0
	v_add_u32_e32 v227, 0x7000, v182
	v_add_u32_e32 v228, 0x8800, v182
	v_permlane32_swap_b32_e32 v3, v4
	v_add_u32_e32 v229, 0x9800, v182
	v_max3_f32 v3, v183, v3, v4
	v_fma_f32 v4, v96, s18, -v3
	v_sub_f32_e32 v0, v183, v3
	v_exp_f32_e32 v183, v4
	v_fma_f32 v4, v97, s18, -v3
	v_exp_f32_e32 v184, v4
	v_fma_f32 v4, v98, s18, -v3
	v_exp_f32_e32 v185, v4
	v_fma_f32 v4, v99, s18, -v3
	v_exp_f32_e32 v186, v4
	v_fma_f32 v5, v100, s18, -v3
	v_add_f32_e32 v4, 0, v183
	v_exp_f32_e32 v187, v5
	v_fma_f32 v5, v101, s18, -v3
	v_add_f32_e32 v4, v184, v4
	v_exp_f32_e32 v192, v5
	v_fma_f32 v5, v102, s18, -v3
	v_add_f32_e32 v4, v185, v4
	v_exp_f32_e32 v193, v5
	v_fma_f32 v5, v103, s18, -v3
	v_add_f32_e32 v4, v186, v4
	v_exp_f32_e32 v103, v5
	v_fma_f32 v5, v104, s18, -v3
	v_add_f32_e32 v4, v187, v4
	v_exp_f32_e32 v104, v5
	v_fma_f32 v5, v105, s18, -v3
	v_add_f32_e32 v4, v192, v4
	v_exp_f32_e32 v105, v5
	v_fma_f32 v5, v106, s18, -v3
	v_add_f32_e32 v4, v193, v4
	v_exp_f32_e32 v106, v5
	v_fma_f32 v5, v107, s18, -v3
	v_add_f32_e32 v4, v103, v4
	v_exp_f32_e32 v107, v5
	v_fma_f32 v5, v108, s18, -v3
	v_add_f32_e32 v4, v104, v4
	v_exp_f32_e32 v108, v5
	v_fma_f32 v5, v109, s18, -v3
	v_add_f32_e32 v4, v105, v4
	v_exp_f32_e32 v109, v5
	v_fma_f32 v5, v110, s18, -v3
	v_add_f32_e32 v4, v106, v4
	v_exp_f32_e32 v110, v5
	v_fma_f32 v5, v111, s18, -v3
	v_add_f32_e32 v4, v107, v4
	v_exp_f32_e32 v111, v5
	v_fma_f32 v5, v80, s18, -v3
	v_add_f32_e32 v4, v108, v4
	v_exp_f32_e32 v204, v5
	v_fma_f32 v5, v81, s18, -v3
	v_add_f32_e32 v4, v109, v4
	v_exp_f32_e32 v205, v5
	v_fma_f32 v5, v82, s18, -v3
	v_add_f32_e32 v4, v110, v4
	v_exp_f32_e32 v206, v5
	v_fma_f32 v5, v83, s18, -v3
	v_add_f32_e32 v4, v111, v4
	v_exp_f32_e32 v207, v5
	v_fma_f32 v5, v84, s18, -v3
	v_exp_f32_e32 v213, v5
	v_fma_f32 v5, v85, s18, -v3
	v_add_f32_e32 v4, v204, v4
	v_exp_f32_e32 v214, v5
	v_fma_f32 v5, v86, s18, -v3
	v_add_f32_e32 v4, v205, v4
	v_exp_f32_e32 v215, v5
	v_fma_f32 v5, v87, s18, -v3
	v_add_f32_e32 v4, v206, v4
	v_exp_f32_e32 v216, v5
	v_fma_f32 v5, v88, s18, -v3
	v_add_f32_e32 v4, v207, v4
	v_exp_f32_e32 v217, v5
	v_fma_f32 v5, v89, s18, -v3
	v_add_f32_e32 v4, v213, v4
	v_exp_f32_e32 v218, v5
	v_fma_f32 v5, v90, s18, -v3
	v_add_f32_e32 v4, v214, v4
	v_exp_f32_e32 v219, v5
	v_fma_f32 v5, v91, s18, -v3
	v_add_f32_e32 v4, v215, v4
	v_exp_f32_e32 v220, v5
	v_fma_f32 v5, v92, s18, -v3
	v_add_f32_e32 v4, v216, v4
	v_exp_f32_e32 v221, v5
	v_fma_f32 v5, v93, s18, -v3
	v_add_f32_e32 v4, v217, v4
	v_exp_f32_e32 v222, v5
	v_fma_f32 v5, v94, s18, -v3
	v_add_f32_e32 v4, v218, v4
	v_exp_f32_e32 v223, v5
	v_fma_f32 v5, v95, s18, -v3
	v_add_f32_e32 v4, v219, v4
	v_exp_f32_e32 v224, v5
	v_add_f32_e32 v4, v220, v4
	v_add_f32_e32 v4, v221, v4
	v_add_f32_e32 v4, v222, v4
	v_add_f32_e32 v4, v223, v4
	v_add_f32_e32 v225, v224, v4
	ds_read2_b64 v[4:7], v226 offset0:128 offset1:130
	ds_read2_b64 v[8:11], v226 offset0:132 offset1:134
	ds_read2_b64 v[12:15], v227 offset0:192 offset1:194
	ds_read2_b64 v[80:83], v228 offset1:2
	ds_read2_b64 v[84:87], v229 offset0:64 offset1:66
	ds_read2_b64 v[88:91], v227 offset0:196 offset1:198
	ds_read2_b64 v[92:95], v228 offset0:4 offset1:6
	ds_read2_b64 v[96:99], v229 offset0:68 offset1:70
	v_exp_f32_e32 v0, v0
	v_cvt_pk_bf16_f32 v100, v183, v184
	v_cvt_pk_bf16_f32 v101, v185, v186
	v_cvt_pk_bf16_f32 v102, v187, v192
	v_pk_mul_f32 v[78:79], v[78:79], v[0:1] op_sel_hi:[1,0]
	v_pk_mul_f32 v[76:77], v[76:77], v[0:1] op_sel_hi:[1,0]
	v_pk_mul_f32 v[74:75], v[74:75], v[0:1] op_sel_hi:[1,0]
	v_pk_mul_f32 v[72:73], v[72:73], v[0:1] op_sel_hi:[1,0]
	v_pk_mul_f32 v[70:71], v[70:71], v[0:1] op_sel_hi:[1,0]
	v_pk_mul_f32 v[68:69], v[68:69], v[0:1] op_sel_hi:[1,0]
	v_pk_mul_f32 v[66:67], v[66:67], v[0:1] op_sel_hi:[1,0]
	v_pk_mul_f32 v[64:65], v[64:65], v[0:1] op_sel_hi:[1,0]
	v_pk_mul_f32 v[62:63], v[62:63], v[0:1] op_sel_hi:[1,0]
	v_pk_mul_f32 v[60:61], v[60:61], v[0:1] op_sel_hi:[1,0]
	v_pk_mul_f32 v[58:59], v[58:59], v[0:1] op_sel_hi:[1,0]
	v_pk_mul_f32 v[56:57], v[56:57], v[0:1] op_sel_hi:[1,0]
	v_pk_mul_f32 v[54:55], v[54:55], v[0:1] op_sel_hi:[1,0]
	v_pk_mul_f32 v[52:53], v[52:53], v[0:1] op_sel_hi:[1,0]
	v_pk_mul_f32 v[50:51], v[50:51], v[0:1] op_sel_hi:[1,0]
	v_pk_mul_f32 v[48:49], v[48:49], v[0:1] op_sel_hi:[1,0]
	v_pk_mul_f32 v[46:47], v[46:47], v[0:1] op_sel_hi:[1,0]
	v_pk_mul_f32 v[44:45], v[44:45], v[0:1] op_sel_hi:[1,0]
	v_pk_mul_f32 v[42:43], v[42:43], v[0:1] op_sel_hi:[1,0]
	v_pk_mul_f32 v[40:41], v[40:41], v[0:1] op_sel_hi:[1,0]
	v_pk_mul_f32 v[38:39], v[38:39], v[0:1] op_sel_hi:[1,0]
	v_pk_mul_f32 v[36:37], v[36:37], v[0:1] op_sel_hi:[1,0]
	v_pk_mul_f32 v[34:35], v[34:35], v[0:1] op_sel_hi:[1,0]
	v_pk_mul_f32 v[32:33], v[32:33], v[0:1] op_sel_hi:[1,0]
	v_pk_mul_f32 v[30:31], v[30:31], v[0:1] op_sel_hi:[1,0]
	v_pk_mul_f32 v[28:29], v[28:29], v[0:1] op_sel_hi:[1,0]
	v_pk_mul_f32 v[26:27], v[26:27], v[0:1] op_sel_hi:[1,0]
	v_pk_mul_f32 v[24:25], v[24:25], v[0:1] op_sel_hi:[1,0]
	v_pk_mul_f32 v[22:23], v[22:23], v[0:1] op_sel_hi:[1,0]
	v_pk_mul_f32 v[20:21], v[20:21], v[0:1] op_sel_hi:[1,0]
	v_pk_mul_f32 v[18:19], v[18:19], v[0:1] op_sel_hi:[1,0]
	v_pk_mul_f32 v[16:17], v[16:17], v[0:1] op_sel_hi:[1,0]
	v_cvt_pk_bf16_f32 v103, v193, v103
	s_waitcnt lgkmcnt(7)
; DI unsigned pk2(float lo, float hi) { const hwf2_t v = {lo, hi}; const hwbf2_t b = __builtin_convertvector(v, hwbf2_t); return __builtin_bit_cast(unsigned, b); }
; #define ATT_LDV(buf, gi) do { const int _kg = (gi) / NDB, _db = (gi) % NDB; _Pragma("unroll") for (int d = 0; d < 4; ++d) { const bf16_t* vp = Vs + (32 * (4 * _db + d) + l31) * VS + 16 * _kg + 4 * hh; \
;                         const u32x2 lo = *(const u32x2*)vp, hi = *(const u32x2*)(vp + 8); Vf[buf][d].x = lo.x; Vf[buf][d].y = lo.y; Vf[buf][d].z = hi.x; Vf[buf][d].w = hi.y; } } while (0)
; template <int DK, int DV, int KT, bool SAMPLE>
; DI void attn_item(CP c, int l, int qb, int h, unsigned char* sm) {
;     ...
;             l_run = l_run * alpha + psum; m_run = mnew;
; #pragma unroll
;             for (int d = 0; d < NDT; ++d) Oacc[d] = Oacc[d] * alpha;
;             {
;                 constexpr int NDB = NDT / 4;
;                 constexpr int NG = 2 * NMT * NDB;
;                 u32x4 Vf[2][4];
;     ...
;                 ATT_LDV(0, 0);
; #pragma unroll
;                 for (int gi = 0; gi < NG; ++gi) { const int kg = gi / NDB, db = gi % NDB, mt = kg >> 1, s2 = kg & 1;
;                     if (gi + 1 < NG) ATT_LDV((gi + 1) & 1, gi + 1);
;                     u32x4 pw; pw.x = pk2(S[mt][8 * s2 + 0], S[mt][8 * s2 + 1]); pw.y = pk2(S[mt][8 * s2 + 2], S[mt][8 * s2 + 3]);
;                     pw.z = pk2(S[mt][8 * s2 + 4], S[mt][8 * s2 + 5]); pw.w = pk2(S[mt][8 * s2 + 6], S[mt][8 * s2 + 7]);
;                     const bf16x8 pf = __builtin_bit_cast(bf16x8, pw);
;                     __builtin_amdgcn_sched_barrier(0);
; #pragma unroll
;                     for (int d = 0; d < 4; ++d) Oacc[4 * db + d] = __builtin_amdgcn_mfma_f32_32x32x16_bf16(__builtin_bit_cast(bf16x8, Vf[gi & 1][d]), pf, Oacc[4 * db + d], 0, 0, 0);
;                     __builtin_amdgcn_sched_barrier(0);
;                 }
	s_nop 0
	v_mfma_f32_32x32x16_bf16 v[64:79], v[4:7], v[100:103], v[64:79]
	s_waitcnt lgkmcnt(5)
	v_mfma_f32_32x32x16_bf16 v[48:63], v[12:15], v[100:103], v[48:63]
	global_load_dwordx4 v[136:139], v[164:165], off
	s_waitcnt lgkmcnt(4)
	v_mfma_f32_32x32x16_bf16 v[32:47], v[80:83], v[100:103], v[32:47]
	s_waitcnt lgkmcnt(3)
	v_mfma_f32_32x32x16_bf16 v[16:31], v[84:87], v[100:103], v[16:31]
	ds_read2_b64 v[4:7], v226 offset0:136 offset1:138
	ds_read2_b64 v[12:15], v227 offset0:200 offset1:202
	ds_read2_b64 v[80:83], v228 offset0:8 offset1:10
	ds_read2_b64 v[84:87], v229 offset0:72 offset1:74
	v_cvt_pk_bf16_f32 v100, v104, v105
	v_cvt_pk_bf16_f32 v101, v106, v107
	v_cvt_pk_bf16_f32 v102, v108, v109
	v_cvt_pk_bf16_f32 v103, v110, v111
	s_nop 1
	v_mfma_f32_32x32x16_bf16 v[64:79], v[8:11], v[100:103], v[64:79]
	s_waitcnt lgkmcnt(6)
	v_mfma_f32_32x32x16_bf16 v[48:63], v[88:91], v[100:103], v[48:63]
	global_load_dwordx4 v[140:143], v[164:165], off offset:32
	s_waitcnt lgkmcnt(5)
	v_mfma_f32_32x32x16_bf16 v[32:47], v[92:95], v[100:103], v[32:47]
	s_waitcnt lgkmcnt(4)
	v_mfma_f32_32x32x16_bf16 v[16:31], v[96:99], v[100:103], v[16:31]
	ds_read2_b64 v[8:11], v226 offset0:140 offset1:142
	ds_read2_b64 v[88:91], v227 offset0:204 offset1:206
	ds_read2_b64 v[92:95], v228 offset0:12 offset1:14
	ds_read2_b64 v[96:99], v229 offset0:76 offset1:78
	v_cvt_pk_bf16_f32 v100, v204, v205
	v_cvt_pk_bf16_f32 v101, v206, v207
	v_cvt_pk_bf16_f32 v102, v213, v214
	v_cvt_pk_bf16_f32 v103, v215, v216
	s_waitcnt lgkmcnt(7)
	s_nop 0
	v_mfma_f32_32x32x16_bf16 v[64:79], v[4:7], v[100:103], v[64:79]
	s_waitcnt lgkmcnt(6)
	v_mfma_f32_32x32x16_bf16 v[48:63], v[12:15], v[100:103], v[48:63]
	global_load_dwordx4 v[144:147], v[164:165], off offset:64
	s_waitcnt lgkmcnt(5)
	v_mfma_f32_32x32x16_bf16 v[32:47], v[80:83], v[100:103], v[32:47]
	s_waitcnt lgkmcnt(4)
	v_mfma_f32_32x32x16_bf16 v[16:31], v[84:87], v[100:103], v[16:31]
	v_cvt_pk_bf16_f32 v4, v217, v218
	v_cvt_pk_bf16_f32 v5, v219, v220
	v_cvt_pk_bf16_f32 v6, v221, v222
	v_cvt_pk_bf16_f32 v7, v223, v224
	s_waitcnt lgkmcnt(3)
	s_nop 0
	v_mfma_f32_32x32x16_bf16 v[64:79], v[8:11], v[4:7], v[64:79]
	s_waitcnt lgkmcnt(2)
	v_mfma_f32_32x32x16_bf16 v[48:63], v[88:91], v[4:7], v[48:63]
	global_load_dwordx4 v[148:151], v[164:165], off offset:96
	s_waitcnt lgkmcnt(1)
	v_mfma_f32_32x32x16_bf16 v[32:47], v[92:95], v[4:7], v[32:47]
	s_waitcnt lgkmcnt(0)
	v_mfma_f32_32x32x16_bf16 v[16:31], v[96:99], v[4:7], v[16:31]
	v_fmac_f32_e32 v225, v177, v0
	v_mov_b32_e32 v177, v225
	v_mov_b32_e32 v183, v3
	s_branch .LBB0_646
